# MLA: the OR reduction of the packed P words as a depth-3 tree instead of a serial 8-link chain
# baseline (speedup 1.0000x reference)
; #define WLK(n) do { asm volatile("s_waitcnt lgkmcnt(" #n ")" ::: "memory"); SBAR(); } while (0)
; #define RDN(S, dd, off) do { const int a_ = rb + (((dd) * 32 + h16) ^ sw); KRD(S##0, a_, off); KRD(S##1, a_, 8192 + (off)); } while (0)
; #define RDR(S, ks) do { const int a_ = rr + (((((ks) * 2 + hi)) ^ (r32 & 7)) << 4); KRD(S##0, a_, 0); KRD(S##1, a_, 4096); } while (0)
; #define MM1(S, d) do { p0 = __builtin_amdgcn_mfma_f32_32x32x16_bf16(S##0, qr[d], p0, 0, 0, 0); p1 = __builtin_amdgcn_mfma_f32_32x32x16_bf16(S##1, qr[d], p1, 0, 0, 0); } while (0)
; __device__ __forceinline__ void partialSM_pre(f32x16& p0, f32x16& p1, float& m_reg, float& alpha) {
;     ...
; #pragma unroll
;     for (int r = 0; r < 16; ++r) p0[r] = __builtin_amdgcn_exp2f(p0[r]);
; }
; __device__ __forceinline__ void finishSM(f32x16& p0, f32x16& p1, float alpha, float& l_reg, bf16x8& pa0, bf16x8& pa1, bf16x8& pa2, bf16x8& pa3) {
; #pragma unroll
;     for (int r = 0; r < 16; ++r) p1[r] = __builtin_amdgcn_exp2f(p1[r]);
;     float ps = 0;
; #pragma unroll
;     for (int r = 0; r < 16; ++r) ps += p0[r];
; #pragma unroll
;     for (int r = 0; r < 16; ++r) ps += p1[r];
;     { auto rr = __builtin_amdgcn_permlane32_swap(__float_as_uint(ps), __float_as_uint(ps), false, false);
;       ps = __uint_as_float(rr[0]) + __uint_as_float(rr[1]); }
;     l_reg = l_reg * alpha + ps;
;     ...
;     PK4(p0, 0, pa0); PK4(p0, 8, pa1); PK4(p1, 0, pa2); PK4(p1, 8, pa3);
; __device__ __forceinline__ void qk_mla(f32x16& p0, f32x16& p1, int kaddr, int r32, int hi, const bf16x8* qr) {
;     const int rb = kaddr + r32 * 256, sw = (r32 & 7) << 4, h16 = hi * 16;
;     const int rr = kaddr + 16384 + r32 * 128;
;     ...
;     bf16x8 A0, A1, B0, B1;
;     RDN(A, 0, 0); RDN(B, 1, 0);
;     WLK(2); MM1(A, 0); RDN(A, 2, 0);
;     WLK(2); MM1(B, 1); RDN(B, 3, 0);
;     WLK(2); MM1(A, 2); RDN(A, 0, 128);
;     WLK(2); MM1(B, 3); RDN(B, 1, 128);
;     WLK(2); MM1(A, 4); RDN(A, 2, 128);
;     WLK(2); MM1(B, 5); RDN(B, 3, 128);
;     WLK(2); MM1(A, 6); RDR(A, 0);
;     WLK(2); MM1(B, 7); RDR(B, 1);
;     WLK(2); MM1(A, 8); RDR(A, 2);
;     WLK(2); MM1(B, 9); RDR(B, 3);
;     WLK(2); MM1(A, 10);
;     WLK(0); MM1(B, 11);
.Lm16_nomask:
	v_exp_f32_e32 v114, v114
	v_exp_f32_e32 v115, v115
	v_exp_f32_e32 v116, v116
	v_exp_f32_e32 v117, v117
	v_exp_f32_e32 v118, v118
	v_exp_f32_e32 v119, v119
	v_exp_f32_e32 v120, v120
	v_exp_f32_e32 v121, v121
	v_exp_f32_e32 v122, v122
	v_exp_f32_e32 v123, v123
	v_exp_f32_e32 v124, v124
	v_exp_f32_e32 v125, v125
	v_exp_f32_e32 v126, v126
	v_exp_f32_e32 v127, v127
	v_exp_f32_e32 v128, v128
	v_exp_f32_e32 v129, v129
	v_exp_f32_e32 v130, v130
	v_exp_f32_e32 v131, v131
	v_exp_f32_e32 v132, v132
	v_exp_f32_e32 v133, v133
	v_exp_f32_e32 v134, v134
	v_exp_f32_e32 v135, v135
	v_exp_f32_e32 v136, v136
	v_exp_f32_e32 v137, v137
	v_exp_f32_e32 v138, v138
	v_exp_f32_e32 v139, v139
	v_exp_f32_e32 v140, v140
	v_exp_f32_e32 v141, v141
	v_exp_f32_e32 v142, v142
	v_exp_f32_e32 v143, v143
	v_exp_f32_e32 v144, v144
	v_exp_f32_e32 v145, v145
	v_cvt_pk_bf16_f32 v164, v114, v115
	v_cvt_pk_bf16_f32 v165, v116, v117
	v_cvt_pk_bf16_f32 v166, v122, v123
	v_cvt_pk_bf16_f32 v167, v124, v125
	v_cvt_pk_bf16_f32 v168, v130, v131
	v_cvt_pk_bf16_f32 v169, v132, v133
	v_cvt_pk_bf16_f32 v170, v138, v139
	v_cvt_pk_bf16_f32 v171, v140, v141
	v_cvt_pk_bf16_f32 v172, v118, v119
	v_cvt_pk_bf16_f32 v173, v120, v121
	v_cvt_pk_bf16_f32 v174, v126, v127
	v_cvt_pk_bf16_f32 v175, v128, v129
	v_cvt_pk_bf16_f32 v176, v134, v135
	v_cvt_pk_bf16_f32 v177, v136, v137
	v_cvt_pk_bf16_f32 v178, v142, v143
	v_cvt_pk_bf16_f32 v179, v144, v145
	v_or3_b32 v220, v164, v165, v166
	v_or3_b32 v221, v167, v168, v169
	v_or3_b32 v222, v170, v171, v172
	v_or3_b32 v223, v173, v174, v175
	v_or3_b32 v158, v176, v177, v178
	v_or3_b32 v220, v220, v221, v222
	v_or3_b32 v223, v223, v158, v179
	v_or_b32_e32 v220, v220, v223
	v_and_b32_e32 v220, 0x40004000, v220
	v_cmp_eq_u32_e32 vcc, 0, v220
	s_cmp_eq_u64 vcc, exec
	s_cbranch_scc1 .Lm16_pv
	ds_read_b128 v[180:183], v228 offset:0
	ds_read_b128 v[184:187], v228 offset:2048
	ds_read_b128 v[188:191], v228 offset:4096
	ds_read_b128 v[192:195], v228 offset:6144
	s_waitcnt lgkmcnt(3)
	v_mfma_f32_16x16x32_bf16 v[114:117], v[180:183], v[66:69], v[208:211]
	v_mfma_f32_16x16x32_bf16 v[118:121], v[180:183], v[90:93], v[212:215]
	ds_read_b128 v[180:183], v229 offset:0
	s_waitcnt lgkmcnt(3)
	v_mfma_f32_16x16x32_bf16 v[122:125], v[184:187], v[66:69], v[208:211]
	v_mfma_f32_16x16x32_bf16 v[126:129], v[184:187], v[90:93], v[212:215]
	ds_read_b128 v[184:187], v229 offset:2048
	s_waitcnt lgkmcnt(3)
	v_mfma_f32_16x16x32_bf16 v[130:133], v[188:191], v[66:69], v[208:211]
	v_mfma_f32_16x16x32_bf16 v[134:137], v[188:191], v[90:93], v[212:215]
	ds_read_b128 v[188:191], v229 offset:4096
	s_waitcnt lgkmcnt(3)
	v_mfma_f32_16x16x32_bf16 v[138:141], v[192:195], v[66:69], v[208:211]
	v_mfma_f32_16x16x32_bf16 v[142:145], v[192:195], v[90:93], v[212:215]
	ds_read_b128 v[192:195], v229 offset:6144
	s_waitcnt lgkmcnt(3)
	v_mfma_f32_16x16x32_bf16 v[114:117], v[180:183], v[70:73], v[114:117]
	v_mfma_f32_16x16x32_bf16 v[118:121], v[180:183], v[94:97], v[118:121]
	ds_read_b128 v[180:183], v228 offset:8192
	s_waitcnt lgkmcnt(3)
	v_mfma_f32_16x16x32_bf16 v[122:125], v[184:187], v[70:73], v[122:125]
	v_mfma_f32_16x16x32_bf16 v[126:129], v[184:187], v[94:97], v[126:129]
	ds_read_b128 v[184:187], v228 offset:10240
	s_waitcnt lgkmcnt(3)
	v_mfma_f32_16x16x32_bf16 v[130:133], v[188:191], v[70:73], v[130:133]
	v_mfma_f32_16x16x32_bf16 v[134:137], v[188:191], v[94:97], v[134:137]
	ds_read_b128 v[188:191], v228 offset:12288
	s_waitcnt lgkmcnt(3)
	v_mfma_f32_16x16x32_bf16 v[138:141], v[192:195], v[70:73], v[138:141]
	v_mfma_f32_16x16x32_bf16 v[142:145], v[192:195], v[94:97], v[142:145]
	ds_read_b128 v[192:195], v228 offset:14336
	s_waitcnt lgkmcnt(3)
	v_mfma_f32_16x16x32_bf16 v[114:117], v[180:183], v[74:77], v[114:117]
	v_mfma_f32_16x16x32_bf16 v[118:121], v[180:183], v[98:101], v[118:121]
	ds_read_b128 v[180:183], v229 offset:8192
	s_waitcnt lgkmcnt(3)
	v_mfma_f32_16x16x32_bf16 v[122:125], v[184:187], v[74:77], v[122:125]
	v_mfma_f32_16x16x32_bf16 v[126:129], v[184:187], v[98:101], v[126:129]
	ds_read_b128 v[184:187], v229 offset:10240
	s_waitcnt lgkmcnt(3)
	v_mfma_f32_16x16x32_bf16 v[130:133], v[188:191], v[74:77], v[130:133]
	v_mfma_f32_16x16x32_bf16 v[134:137], v[188:191], v[98:101], v[134:137]
	ds_read_b128 v[188:191], v229 offset:12288
	s_waitcnt lgkmcnt(3)
	v_mfma_f32_16x16x32_bf16 v[138:141], v[192:195], v[74:77], v[138:141]
	v_mfma_f32_16x16x32_bf16 v[142:145], v[192:195], v[98:101], v[142:145]
	ds_read_b128 v[192:195], v229 offset:14336
	s_waitcnt lgkmcnt(3)
	v_mfma_f32_16x16x32_bf16 v[114:117], v[180:183], v[78:81], v[114:117]
	v_mfma_f32_16x16x32_bf16 v[118:121], v[180:183], v[102:105], v[118:121]
	ds_read_b128 v[180:183], v228 offset:16384
	s_waitcnt lgkmcnt(3)
	v_mfma_f32_16x16x32_bf16 v[122:125], v[184:187], v[78:81], v[122:125]
	v_mfma_f32_16x16x32_bf16 v[126:129], v[184:187], v[102:105], v[126:129]
	ds_read_b128 v[184:187], v228 offset:18432
	s_waitcnt lgkmcnt(3)
	v_mfma_f32_16x16x32_bf16 v[130:133], v[188:191], v[78:81], v[130:133]
	v_mfma_f32_16x16x32_bf16 v[134:137], v[188:191], v[102:105], v[134:137]
	ds_read_b128 v[188:191], v228 offset:20480
	s_waitcnt lgkmcnt(3)
	v_mfma_f32_16x16x32_bf16 v[138:141], v[192:195], v[78:81], v[138:141]
	v_mfma_f32_16x16x32_bf16 v[142:145], v[192:195], v[102:105], v[142:145]
	ds_read_b128 v[192:195], v228 offset:22528
	s_waitcnt lgkmcnt(3)
	v_mfma_f32_16x16x32_bf16 v[114:117], v[180:183], v[82:85], v[114:117]
	v_mfma_f32_16x16x32_bf16 v[118:121], v[180:183], v[106:109], v[118:121]
	ds_read_b128 v[180:183], v229 offset:16384
	s_waitcnt lgkmcnt(3)
	v_mfma_f32_16x16x32_bf16 v[122:125], v[184:187], v[82:85], v[122:125]
	v_mfma_f32_16x16x32_bf16 v[126:129], v[184:187], v[106:109], v[126:129]
	ds_read_b128 v[184:187], v229 offset:18432
	s_waitcnt lgkmcnt(3)
	v_mfma_f32_16x16x32_bf16 v[130:133], v[188:191], v[82:85], v[130:133]
	v_mfma_f32_16x16x32_bf16 v[134:137], v[188:191], v[106:109], v[134:137]
	ds_read_b128 v[188:191], v229 offset:20480
	s_waitcnt lgkmcnt(3)
	v_mfma_f32_16x16x32_bf16 v[138:141], v[192:195], v[82:85], v[138:141]
	v_mfma_f32_16x16x32_bf16 v[142:145], v[192:195], v[106:109], v[142:145]
	ds_read_b128 v[192:195], v229 offset:22528
	s_waitcnt lgkmcnt(3)
	v_mfma_f32_16x16x32_bf16 v[114:117], v[180:183], v[86:89], v[114:117]
	v_mfma_f32_16x16x32_bf16 v[118:121], v[180:183], v[110:113], v[118:121]
	s_waitcnt lgkmcnt(2)
	v_mfma_f32_16x16x32_bf16 v[122:125], v[184:187], v[86:89], v[122:125]
	v_mfma_f32_16x16x32_bf16 v[126:129], v[184:187], v[110:113], v[126:129]
	s_waitcnt lgkmcnt(1)
	v_mfma_f32_16x16x32_bf16 v[130:133], v[188:191], v[86:89], v[130:133]
	v_mfma_f32_16x16x32_bf16 v[134:137], v[188:191], v[110:113], v[134:137]
	s_waitcnt lgkmcnt(0)
	v_mfma_f32_16x16x32_bf16 v[138:141], v[192:195], v[86:89], v[138:141]
	v_mfma_f32_16x16x32_bf16 v[142:145], v[192:195], v[110:113], v[142:145]
	s_nop 7
	s_add_u32 s36, s42, 63
	s_cmp_gt_u32 s36, s43
	s_cbranch_scc0 .Lm16_nomask_s
; __device__ __forceinline__ void mask_tile(f32x16& p0, f32x16& p1, int dq, unsigned W) {
;     const float NEG = -__builtin_inff();
; #pragma unroll
;     for (int r = 0; r < 16; ++r) { const int c = (r & 3) + 8 * (r >> 2);
;         if ((unsigned)(dq - c) >= W) p0[r] = NEG;
;         if ((unsigned)(dq - c - 32) >= W) p1[r] = NEG; }
; }
	s_sub_u32 s36, s43, s42
	v_add_u32_e32 v244, s36, v243
	v_cmp_gt_i32_e32 vcc, 0, v244
	s_nop 1
	v_cndmask_b32_e32 v114, v114, v245, vcc
	v_cmp_gt_i32_e32 vcc, 1, v244
	s_nop 1
	v_cndmask_b32_e32 v115, v115, v245, vcc
	v_cmp_gt_i32_e32 vcc, 2, v244
	s_nop 1
	v_cndmask_b32_e32 v116, v116, v245, vcc
	v_cmp_gt_i32_e32 vcc, 3, v244
	s_nop 1
	v_cndmask_b32_e32 v117, v117, v245, vcc
	v_cmp_gt_i32_e32 vcc, -16, v244
	s_nop 1
	v_cndmask_b32_e32 v118, v118, v245, vcc
	v_cmp_gt_i32_e32 vcc, -15, v244
	s_nop 1
	v_cndmask_b32_e32 v119, v119, v245, vcc
	v_cmp_gt_i32_e32 vcc, -14, v244
	s_nop 1
	v_cndmask_b32_e32 v120, v120, v245, vcc
	v_cmp_gt_i32_e32 vcc, -13, v244
	s_nop 1
	v_cndmask_b32_e32 v121, v121, v245, vcc
	v_cmp_gt_i32_e32 vcc, 16, v244
	s_nop 1
	v_cndmask_b32_e32 v122, v122, v245, vcc
	v_cmp_gt_i32_e32 vcc, 17, v244
	s_nop 1
	v_cndmask_b32_e32 v123, v123, v245, vcc
	v_cmp_gt_i32_e32 vcc, 18, v244
	s_nop 1
	v_cndmask_b32_e32 v124, v124, v245, vcc
	v_cmp_gt_i32_e32 vcc, 19, v244
	s_nop 1
	v_cndmask_b32_e32 v125, v125, v245, vcc
	v_cmp_gt_i32_e32 vcc, 0, v244
	s_nop 1
	v_cndmask_b32_e32 v126, v126, v245, vcc
	v_cmp_gt_i32_e32 vcc, 1, v244
	s_nop 1
	v_cndmask_b32_e32 v127, v127, v245, vcc
	v_cmp_gt_i32_e32 vcc, 2, v244
	s_nop 1
	v_cndmask_b32_e32 v128, v128, v245, vcc
	v_cmp_gt_i32_e32 vcc, 3, v244
	s_nop 1
	v_cndmask_b32_e32 v129, v129, v245, vcc
	v_cmp_gt_i32_e32 vcc, 32, v244
	s_nop 1
	v_cndmask_b32_e32 v130, v130, v245, vcc
	v_cmp_gt_i32_e32 vcc, 33, v244
	s_nop 1
	v_cndmask_b32_e32 v131, v131, v245, vcc
	v_cmp_gt_i32_e32 vcc, 34, v244
	s_nop 1
	v_cndmask_b32_e32 v132, v132, v245, vcc
	v_cmp_gt_i32_e32 vcc, 35, v244
	s_nop 1
	v_cndmask_b32_e32 v133, v133, v245, vcc
	v_cmp_gt_i32_e32 vcc, 16, v244
	s_nop 1
	v_cndmask_b32_e32 v134, v134, v245, vcc
	v_cmp_gt_i32_e32 vcc, 17, v244
	s_nop 1
	v_cndmask_b32_e32 v135, v135, v245, vcc
	v_cmp_gt_i32_e32 vcc, 18, v244
	s_nop 1
	v_cndmask_b32_e32 v136, v136, v245, vcc
	v_cmp_gt_i32_e32 vcc, 19, v244
	s_nop 1
	v_cndmask_b32_e32 v137, v137, v245, vcc
	v_cmp_gt_i32_e32 vcc, 48, v244
	s_nop 1
	v_cndmask_b32_e32 v138, v138, v245, vcc
	v_cmp_gt_i32_e32 vcc, 49, v244
	s_nop 1
	v_cndmask_b32_e32 v139, v139, v245, vcc
	v_cmp_gt_i32_e32 vcc, 50, v244
	s_nop 1
	v_cndmask_b32_e32 v140, v140, v245, vcc
	v_cmp_gt_i32_e32 vcc, 51, v244
	s_nop 1
	v_cndmask_b32_e32 v141, v141, v245, vcc
	v_cmp_gt_i32_e32 vcc, 32, v244
	s_nop 1
	v_cndmask_b32_e32 v142, v142, v245, vcc
	v_cmp_gt_i32_e32 vcc, 33, v244
	s_nop 1
	v_cndmask_b32_e32 v143, v143, v245, vcc
	v_cmp_gt_i32_e32 vcc, 34, v244
	s_nop 1
	v_cndmask_b32_e32 v144, v144, v245, vcc
	v_cmp_gt_i32_e32 vcc, 35, v244
	s_nop 1
	v_cndmask_b32_e32 v145, v145, v245, vcc
